# sample w_out task: all 16 operand loads issued up front, counted waits before the 8 MFMAs
# baseline (speedup 1.0000x reference)
; DEV unsigned pk2(float lo, float hi) { return (unsigned)f2bf(lo) | ((unsigned)f2bf(hi) << 16); }
; #define LAS __attribute__((address_space(3)))
; template <bool F32A, bool PAIR, class Epi> DEV void sgemm_wg(const void* Aptr, int lda, const bf16_t* Bt, int ldb, int K, int n0, int n1, int wave, int lane, LAS float* red, Epi epi) {
;     ...
;     for (int k = kb; k < kb + kper; k += 16) {
;         bf16x8 a;
;         if (F32A) { const float* ap = (const float*)Aptr + (size_t)r32 * lda + k + 8 * hi; const f32x4 x0 = *(const f32x4*)ap, x1 = *(const f32x4*)(ap + 4);
;             ss += (x0.x * x0.x + x0.y * x0.y) + (x0.z * x0.z + x0.w * x0.w) + (x1.x * x1.x + x1.y * x1.y) + (x1.z * x1.z + x1.w * x1.w);
;             u32x4 w; w.x = pk2(x0.x, x0.y); w.y = pk2(x0.z, x0.w); w.z = pk2(x1.x, x1.y); w.w = pk2(x1.z, x1.w); a = __builtin_bit_cast(bf16x8, w); }
;         else a = *(const bf16x8*)((const bf16_t*)Aptr + (size_t)r32 * lda + k + 8 * hi);
;         acc0 = __builtin_amdgcn_mfma_f32_32x32x16_bf16(a, *(const bf16x8*)(bp0 + k), acc0, 0, 0, 0);
;         if (PAIR) acc1 = __builtin_amdgcn_mfma_f32_32x32x16_bf16(a, *(const bf16x8*)(bp1 + k), acc1, 0, 0, 0);
;     }
;     LAS float* ssw = red + 2 * 8 * 1024;
; #pragma unroll
;     for (int r = 0; r < 16; ++r) { red[(wave * 16 + r) * 64 + lane] = acc0[r]; if (PAIR) red[8 * 1024 + (wave * 16 + r) * 64 + lane] = acc1[r]; }
;     if (F32A) { ss += shfl_xor_(ss, 32); if (lane < 32) ssw[wave * 32 + lane] = ss; }
;     __syncthreads();
; #pragma unroll
;     for (int i = 0; i < 2; ++i) { const int e = wave * 64 + lane + 512 * i, r = e >> 6, ln = e & 63, row = crow(r, ln >> 5);
;         float v0 = 0.f, v1 = 0.f, sq = 0.f;
; #pragma unroll
;         for (int w = 0; w < 8; ++w) { v0 += red[(w * 16 + r) * 64 + ln]; if (PAIR) v1 += red[8 * 1024 + (w * 16 + r) * 64 + ln]; if (F32A) sq += ssw[w * 32 + row]; }
;         epi(row, ln & 31, v0, v1, sq); }
; __global__ void __launch_bounds__(512, 2) mk_fwd(MKArgs args) {
;     ...
;             { PHASE_IDS for (int k = G - 1 - bx; k < DM / 32; k += G) {
;                 sgemm_wg<false, false>(ws + WS_MIXS, DM, (const bf16_t*)(wl + WL_OUT), DM, DM, 32 * k, 0, wave, lane, (LAS float*)(ldsl + RING_OFF), [&](int row, int c, float v, float, float) { const size_t o = (size_t)row * DM + 32 * k + c; xs[o] = xin_s[o] + v; });
;                 if (mrg) wg_post(ctl + CW_S4 + 64 * l, wave_s); } }
.LBB0_1933:
	v_add_u32_e32 v2, s14, v18
	v_ashrrev_i32_e32 v3, 31, v2
	v_lshlrev_b64 v[6:7], 11, v[2:3]
	s_barrier
	v_lshl_add_u64 v[36:37], v[26:27], 0, v[6:7]
	global_load_dwordx4 v[42:45], v[20:21], off
	global_load_dwordx4 v[46:49], v[36:37], off
	global_load_dwordx4 v[50:53], v[20:21], off offset:32
	global_load_dwordx4 v[54:57], v[36:37], off offset:32
	global_load_dwordx4 v[58:61], v[20:21], off offset:64
	global_load_dwordx4 v[62:65], v[36:37], off offset:64
	global_load_dwordx4 v[66:69], v[20:21], off offset:96
	global_load_dwordx4 v[70:73], v[36:37], off offset:96
	global_load_dwordx4 v[74:77], v[20:21], off offset:128
	global_load_dwordx4 v[78:81], v[36:37], off offset:128
	global_load_dwordx4 v[82:85], v[20:21], off offset:160
	global_load_dwordx4 v[86:89], v[36:37], off offset:160
	global_load_dwordx4 v[90:93], v[20:21], off offset:192
	global_load_dwordx4 v[94:97], v[36:37], off offset:192
	global_load_dwordx4 v[98:101], v[20:21], off offset:224
	global_load_dwordx4 v[102:105], v[36:37], off offset:224
	s_ashr_i32 s8, s14, 31
	s_andn2_b64 vcc, exec, s[0:1]
	s_waitcnt vmcnt(14)
	v_mfma_f32_32x32x16_bf16 v[2:17], v[42:45], v[46:49], 0
	s_waitcnt vmcnt(12)
	v_mfma_f32_32x32x16_bf16 v[2:17], v[50:53], v[54:57], v[2:17]
	s_waitcnt vmcnt(10)
	v_mfma_f32_32x32x16_bf16 v[2:17], v[58:61], v[62:65], v[2:17]
	s_waitcnt vmcnt(8)
	v_mfma_f32_32x32x16_bf16 v[2:17], v[66:69], v[70:73], v[2:17]
	s_waitcnt vmcnt(6)
	v_mfma_f32_32x32x16_bf16 v[2:17], v[74:77], v[78:81], v[2:17]
	s_waitcnt vmcnt(4)
	v_mfma_f32_32x32x16_bf16 v[2:17], v[82:85], v[86:89], v[2:17]
	s_waitcnt vmcnt(2)
	v_mfma_f32_32x32x16_bf16 v[2:17], v[90:93], v[94:97], v[2:17]
	s_waitcnt vmcnt(0)
	v_mfma_f32_32x32x16_bf16 v[2:17], v[98:101], v[102:105], v[2:17]
	v_add_u32_e32 v28, s12, v19
	s_nop 10
	ds_write2st64_b32 v28, v2, v3 offset1:1
	ds_write2st64_b32 v28, v4, v5 offset0:2 offset1:3
	ds_write2st64_b32 v28, v6, v7 offset0:4 offset1:5
	ds_write2st64_b32 v28, v8, v9 offset0:6 offset1:7
	ds_write2st64_b32 v28, v10, v11 offset0:8 offset1:9
	ds_write2st64_b32 v28, v12, v13 offset0:10 offset1:11
	ds_write2st64_b32 v28, v14, v15 offset0:12 offset1:13
	ds_write2st64_b32 v28, v16, v17 offset0:14 offset1:15
	s_waitcnt lgkmcnt(0)
	s_barrier
	ds_read2st64_b32 v[4:5], v0 offset1:8
	ds_read2st64_b32 v[6:7], v0 offset0:16 offset1:24
	v_mov_b32_e32 v3, s8
	v_or_b32_e32 v2, s14, v18
	v_lshl_add_u64 v[30:31], v[2:3], 0, v[22:23]
	v_lshlrev_b64 v[30:31], 2, v[30:31]
	s_waitcnt lgkmcnt(1)
	v_add_f32_e32 v4, 0, v4
	v_lshl_add_u64 v[32:33], s[4:5], 0, v[30:31]
	s_waitcnt lgkmcnt(0)
	v_add_f32_e32 v4, v4, v6
	global_load_dword v6, v[32:33], off
	ds_read2st64_b32 v[8:9], v0 offset0:32 offset1:40
	ds_read2st64_b32 v[10:11], v0 offset0:48 offset1:56
	ds_read2st64_b32 v[12:13], v0 offset0:64 offset1:72
	ds_read2st64_b32 v[14:15], v0 offset0:80 offset1:88
	ds_read2st64_b32 v[16:17], v0 offset0:96 offset1:104
	s_waitcnt lgkmcnt(4)
	v_add_f32_e32 v4, v4, v8
	ds_read2st64_b32 v[28:29], v0 offset0:112 offset1:120
	s_waitcnt lgkmcnt(4)
	v_add_f32_e32 v4, v4, v10
	s_waitcnt lgkmcnt(3)
	v_add_f32_e32 v4, v4, v12
	s_waitcnt lgkmcnt(2)
	v_add_f32_e32 v4, v4, v14
	s_waitcnt lgkmcnt(1)
	v_add_f32_e32 v4, v4, v16
	s_waitcnt lgkmcnt(0)
	v_add_f32_e32 v4, v4, v28
	v_lshl_add_u64 v[30:31], s[2:3], 0, v[30:31]
	v_lshl_add_u64 v[2:3], v[2:3], 0, v[24:25]
	v_lshlrev_b64 v[2:3], 2, v[2:3]
	s_waitcnt vmcnt(0)
	v_add_f32_e32 v4, v4, v6
	global_store_dword v[30:31], v4, off
	v_add_f32_e32 v4, 0, v5
	v_add_f32_e32 v4, v4, v7
	v_add_f32_e32 v4, v4, v9
	v_add_f32_e32 v4, v4, v11
	v_add_f32_e32 v4, v4, v13
	v_add_f32_e32 v4, v4, v15
	v_add_f32_e32 v4, v4, v17
	v_add_f32_e32 v6, v4, v29
	v_lshl_add_u64 v[4:5], s[4:5], 0, v[2:3]
	global_load_dword v4, v[4:5], off
	v_lshl_add_u64 v[2:3], s[2:3], 0, v[2:3]
	s_waitcnt vmcnt(0)
	v_add_f32_e32 v4, v6, v4
	global_store_dword v[2:3], v4, off
	s_cbranch_vccnz .LBB0_1932
	v_readlane_b32 s8, v254, 40
	v_readlane_b32 s9, v254, 41
	s_and_b64 vcc, exec, s[8:9]
	s_barrier
	s_cbranch_vccnz .LBB0_1932
	v_mbcnt_lo_u32_b32 v2, -1, 0
	v_mbcnt_hi_u32_b32 v2, -1, v2
	s_nop 0
	v_cmp_eq_u32_e32 vcc, 0, v2
	s_and_saveexec_b64 s[8:9], vcc
	s_cbranch_execz .LBB0_1931
	s_mov_b64 s[10:11], exec
	v_mbcnt_lo_u32_b32 v2, s10, 0
	buffer_wbl2 sc1
	s_waitcnt vmcnt(0)
	s_waitcnt vmcnt(0)
	v_mbcnt_hi_u32_b32 v2, s11, v2
	v_cmp_eq_u32_e32 vcc, 0, v2
	s_and_b64 s[16:17], exec, vcc
	s_mov_b64 exec, s[16:17]
	s_cbranch_execz .LBB0_1931
	s_bcnt1_i32_b64 s10, s[10:11]
	v_mov_b32_e32 v2, s10
	global_atomic_add v1, v2, s[6:7]
	s_branch .LBB0_1931
